# P5 merge: term-A rows 0-3 (of 8) kept in spare VGPRs across the term-B unit
# baseline (speedup 1.0000x reference)
.Lp5sk_2:
	v_lshlrev_b64 v[80:81], 10, v[84:85]
	v_lshl_add_u64 v[80:81], v[140:141], 0, v[80:81]
	global_load_dwordx4 v[80:83], v[80:81], off
	v_lshlrev_b64 v[84:85], 11, v[84:85]
	v_lshl_add_u64 v[84:85], s[10:11], 0, v[84:85]
	s_and_b64 vcc, exec, s[6:7]
	s_waitcnt vmcnt(0)
	v_cvt_f32_ubyte1_e32 v87, v80
	v_cvt_f32_ubyte0_e32 v86, v80
	v_cvt_f32_ubyte3_e32 v89, v80
	v_cvt_f32_ubyte2_e32 v88, v80
	v_cvt_f32_ubyte1_e32 v91, v81
	v_cvt_f32_ubyte0_e32 v90, v81
	v_cvt_f32_ubyte3_e32 v93, v81
	v_cvt_f32_ubyte2_e32 v92, v81
	v_cvt_f32_ubyte1_e32 v81, v82
	v_cvt_f32_ubyte0_e32 v80, v82
	v_cvt_f32_ubyte3_e32 v95, v82
	v_cvt_f32_ubyte2_e32 v94, v82
	v_cvt_f32_ubyte1_e32 v97, v83
	v_cvt_f32_ubyte0_e32 v96, v83
	v_cvt_f32_ubyte3_e32 v99, v83
	v_cvt_f32_ubyte2_e32 v98, v83
	v_pk_mul_f32 v[82:83], v[86:87], s[18:19] op_sel_hi:[1,0]
	v_pk_mul_f32 v[86:87], v[88:89], s[18:19] op_sel_hi:[1,0]
	v_pk_mul_f32 v[88:89], v[90:91], s[18:19] op_sel_hi:[1,0]
	v_pk_mul_f32 v[90:91], v[92:93], s[18:19] op_sel_hi:[1,0]
	v_pk_mul_f32 v[92:93], v[80:81], s[18:19] op_sel_hi:[1,0]
	v_pk_mul_f32 v[94:95], v[94:95], s[18:19] op_sel_hi:[1,0]
	v_pk_mul_f32 v[96:97], v[96:97], s[18:19] op_sel_hi:[1,0]
	v_pk_mul_f32 v[98:99], v[98:99], s[18:19] op_sel_hi:[1,0]
	v_pk_mul_f32 v[76:77], v[76:77], v[82:83]
	v_pk_mul_f32 v[78:79], v[78:79], v[86:87]
	v_pk_mul_f32 v[80:81], v[72:73], v[88:89]
	v_pk_mul_f32 v[74:75], v[74:75], v[90:91]
	v_pk_mul_f32 v[72:73], v[68:69], v[92:93]
	v_pk_mul_f32 v[70:71], v[70:71], v[94:95]
	v_pk_mul_f32 v[68:69], v[64:65], v[96:97]
	v_pk_mul_f32 v[66:67], v[66:67], v[98:99]
	v_lshl_add_u64 v[64:65], v[138:139], 1, v[84:85]
	s_cbranch_vccnz .LBB0_1277
	v_mov_b64_e32 v[82:83], v[250:251]
	v_mov_b64_e32 v[84:85], v[252:253]
	v_mov_b64_e32 v[86:87], v[254:255]
	v_mov_b32_e32 v88, v241
	v_mov_b32_e32 v89, v189
	s_waitcnt vmcnt(0)
	v_lshlrev_b32_e32 v90, 16, v82
	v_and_b32_e32 v91, 0xffff0000, v82
	v_lshlrev_b32_e32 v82, 16, v83
	v_and_b32_e32 v83, 0xffff0000, v83
	v_lshlrev_b32_e32 v92, 16, v84
	v_and_b32_e32 v93, 0xffff0000, v84
	v_lshlrev_b32_e32 v84, 16, v85
	v_and_b32_e32 v85, 0xffff0000, v85
	v_lshlrev_b32_e32 v94, 16, v86
	v_and_b32_e32 v95, 0xffff0000, v86
	v_lshlrev_b32_e32 v86, 16, v87
	v_and_b32_e32 v87, 0xffff0000, v87
	v_lshlrev_b32_e32 v96, 16, v88
	v_and_b32_e32 v97, 0xffff0000, v88
	v_lshlrev_b32_e32 v88, 16, v89
	v_and_b32_e32 v89, 0xffff0000, v89
	v_pk_add_f32 v[76:77], v[76:77], v[90:91]
	v_pk_add_f32 v[78:79], v[78:79], v[82:83]
	v_pk_add_f32 v[80:81], v[80:81], v[92:93]
	v_pk_add_f32 v[74:75], v[74:75], v[84:85]
	v_pk_add_f32 v[72:73], v[72:73], v[94:95]
	v_pk_add_f32 v[70:71], v[70:71], v[86:87]
	v_pk_add_f32 v[68:69], v[68:69], v[96:97]
	v_pk_add_f32 v[66:67], v[66:67], v[88:89]
.LBB0_1277:
	v_cvt_pk_bf16_f32 v76, v76, v77
	v_cvt_pk_bf16_f32 v77, v78, v79
	v_cvt_pk_bf16_f32 v79, v74, v75
	v_cvt_pk_bf16_f32 v74, v68, v69
	v_add_u32_e32 v68, 0x80, v142
	v_cvt_pk_bf16_f32 v78, v80, v81
	v_ashrrev_i32_e32 v69, 31, v68
	v_cvt_pk_bf16_f32 v72, v72, v73
	v_cvt_pk_bf16_f32 v73, v70, v71
	v_cvt_pk_bf16_f32 v75, v66, v67
	s_andn2_b64 vcc, exec, s[4:5]
	s_cbranch_vccz .Lp5st_3
	v_mov_b64_e32 v[250:251], v[76:77]
	v_mov_b64_e32 v[252:253], v[78:79]
	v_mov_b64_e32 v[254:255], v[72:73]
	v_mov_b32_e32 v241, v74
	v_mov_b32_e32 v189, v75
	s_branch .Lp5sk_3
.Lp5st_3:
	global_store_dwordx4 v[64:65], v[76:79], off
	global_store_dwordx4 v[64:65], v[72:75], off offset:16
.Lp5sk_3:
	v_lshlrev_b64 v[64:65], 10, v[68:69]
	v_lshl_add_u64 v[64:65], v[140:141], 0, v[64:65]
	global_load_dwordx4 v[64:67], v[64:65], off
	v_lshlrev_b64 v[68:69], 11, v[68:69]
	v_lshl_add_u64 v[68:69], s[10:11], 0, v[68:69]
	s_and_b64 vcc, exec, s[6:7]
	s_waitcnt vmcnt(0)
	v_cvt_f32_ubyte1_e32 v71, v64
	v_cvt_f32_ubyte0_e32 v70, v64
	v_cvt_f32_ubyte3_e32 v73, v64
	v_cvt_f32_ubyte2_e32 v72, v64
	v_cvt_f32_ubyte1_e32 v75, v65
	v_cvt_f32_ubyte0_e32 v74, v65
	v_cvt_f32_ubyte3_e32 v77, v65
	v_cvt_f32_ubyte2_e32 v76, v65
	v_cvt_f32_ubyte1_e32 v65, v66
	v_cvt_f32_ubyte0_e32 v64, v66
	v_cvt_f32_ubyte3_e32 v79, v66
	v_cvt_f32_ubyte2_e32 v78, v66
	v_cvt_f32_ubyte1_e32 v81, v67
	v_cvt_f32_ubyte0_e32 v80, v67
	v_cvt_f32_ubyte3_e32 v83, v67
	v_cvt_f32_ubyte2_e32 v82, v67
	v_pk_mul_f32 v[66:67], v[70:71], s[18:19] op_sel_hi:[1,0]
	v_pk_mul_f32 v[70:71], v[72:73], s[18:19] op_sel_hi:[1,0]
	v_pk_mul_f32 v[72:73], v[74:75], s[18:19] op_sel_hi:[1,0]
	v_pk_mul_f32 v[74:75], v[76:77], s[18:19] op_sel_hi:[1,0]
	v_pk_mul_f32 v[76:77], v[64:65], s[18:19] op_sel_hi:[1,0]
	v_pk_mul_f32 v[78:79], v[78:79], s[18:19] op_sel_hi:[1,0]
	v_pk_mul_f32 v[80:81], v[80:81], s[18:19] op_sel_hi:[1,0]
	v_pk_mul_f32 v[82:83], v[82:83], s[18:19] op_sel_hi:[1,0]
	v_pk_mul_f32 v[60:61], v[60:61], v[66:67]
	v_pk_mul_f32 v[62:63], v[62:63], v[70:71]
	v_pk_mul_f32 v[64:65], v[56:57], v[72:73]
	v_pk_mul_f32 v[58:59], v[58:59], v[74:75]
	v_pk_mul_f32 v[56:57], v[52:53], v[76:77]
	v_pk_mul_f32 v[54:55], v[54:55], v[78:79]
	v_pk_mul_f32 v[52:53], v[48:49], v[80:81]
	v_pk_mul_f32 v[50:51], v[50:51], v[82:83]
	v_lshl_add_u64 v[48:49], v[138:139], 1, v[68:69]
	s_cbranch_vccnz .LBB0_1279
	global_load_dwordx4 v[66:69], v[48:49], off
	global_load_dwordx4 v[70:73], v[48:49], off offset:16
	s_waitcnt vmcnt(0)
	v_lshlrev_b32_e32 v74, 16, v66
	v_and_b32_e32 v75, 0xffff0000, v66
	v_lshlrev_b32_e32 v66, 16, v67
	v_and_b32_e32 v67, 0xffff0000, v67
	v_lshlrev_b32_e32 v76, 16, v68
	v_and_b32_e32 v77, 0xffff0000, v68
	v_lshlrev_b32_e32 v68, 16, v69
	v_and_b32_e32 v69, 0xffff0000, v69
	v_lshlrev_b32_e32 v78, 16, v70
	v_and_b32_e32 v79, 0xffff0000, v70
	v_lshlrev_b32_e32 v70, 16, v71
	v_and_b32_e32 v71, 0xffff0000, v71
	v_lshlrev_b32_e32 v80, 16, v72
	v_and_b32_e32 v81, 0xffff0000, v72
	v_lshlrev_b32_e32 v72, 16, v73
	v_and_b32_e32 v73, 0xffff0000, v73
	v_pk_add_f32 v[60:61], v[60:61], v[74:75]
	v_pk_add_f32 v[62:63], v[62:63], v[66:67]
	v_pk_add_f32 v[64:65], v[64:65], v[76:77]
	v_pk_add_f32 v[58:59], v[58:59], v[68:69]
	v_pk_add_f32 v[56:57], v[56:57], v[78:79]
	v_pk_add_f32 v[54:55], v[54:55], v[70:71]
	v_pk_add_f32 v[52:53], v[52:53], v[80:81]
	v_pk_add_f32 v[50:51], v[50:51], v[72:73]

	.amdhsa_kernel _Z10fwd_kernel4Args
		.amdhsa_group_segment_fixed_size 0
		.amdhsa_private_segment_fixed_size 0
		.amdhsa_kernarg_size 528
		.amdhsa_user_sgpr_count 2
		.amdhsa_user_sgpr_dispatch_ptr 0
		.amdhsa_user_sgpr_queue_ptr 0
		.amdhsa_user_sgpr_kernarg_segment_ptr 1
		.amdhsa_user_sgpr_dispatch_id 0
		.amdhsa_user_sgpr_kernarg_preload_length 0
		.amdhsa_user_sgpr_kernarg_preload_offset 0
		.amdhsa_user_sgpr_private_segment_size 0
		.amdhsa_uses_dynamic_stack 0
		.amdhsa_enable_private_segment 0
		.amdhsa_system_sgpr_workgroup_id_x 1
		.amdhsa_system_sgpr_workgroup_id_y 0
		.amdhsa_system_sgpr_workgroup_id_z 0
		.amdhsa_system_sgpr_workgroup_info 0
		.amdhsa_system_vgpr_workitem_id 2
		.amdhsa_next_free_vgpr 256
		.amdhsa_next_free_sgpr 102
		.amdhsa_accum_offset 256
		.amdhsa_reserve_vcc 1
		.amdhsa_float_round_mode_32 0
		.amdhsa_float_round_mode_16_64 0
		.amdhsa_float_denorm_mode_32 3
		.amdhsa_float_denorm_mode_16_64 3
		.amdhsa_dx10_clamp 1
		.amdhsa_ieee_mode 1
		.amdhsa_fp16_overflow 0
		.amdhsa_tg_split 0
		.amdhsa_exception_fp_ieee_invalid_op 0
		.amdhsa_exception_fp_denorm_src 0
		.amdhsa_exception_fp_ieee_div_zero 0
		.amdhsa_exception_fp_ieee_overflow 0
		.amdhsa_exception_fp_ieee_underflow 0
		.amdhsa_exception_fp_ieee_inexact 0
		.amdhsa_exception_int_div_zero 0
	.end_amdhsa_kernel

amdhsa.kernels:
  - .agpr_count:     0
    .args:
      - .offset:         0
        .size:           272
        .value_kind:     by_value
      - .offset:         272
        .size:           4
        .value_kind:     hidden_block_count_x
      - .offset:         276
        .size:           4
        .value_kind:     hidden_block_count_y
      - .offset:         280
        .size:           4
        .value_kind:     hidden_block_count_z
      - .offset:         284
        .size:           2
        .value_kind:     hidden_group_size_x
      - .offset:         286
        .size:           2
        .value_kind:     hidden_group_size_y
      - .offset:         288
        .size:           2
        .value_kind:     hidden_group_size_z
      - .offset:         290
        .size:           2
        .value_kind:     hidden_remainder_x
      - .offset:         292
        .size:           2
        .value_kind:     hidden_remainder_y
      - .offset:         294
        .size:           2
        .value_kind:     hidden_remainder_z
      - .offset:         312
        .size:           8
        .value_kind:     hidden_global_offset_x
      - .offset:         320
        .size:           8
        .value_kind:     hidden_global_offset_y
      - .offset:         328
        .size:           8
        .value_kind:     hidden_global_offset_z
      - .offset:         336
        .size:           2
        .value_kind:     hidden_grid_dims
      - .offset:         360
        .size:           8
        .value_kind:     hidden_multigrid_sync_arg
      - .offset:         392
        .size:           4
        .value_kind:     hidden_dynamic_lds_size
    .group_segment_fixed_size: 0
    .kernarg_segment_align: 8
    .kernarg_segment_size: 528
    .language:       OpenCL C
    .language_version:
      - 2
      - 0
    .max_flat_workgroup_size: 512
    .name:           _Z10fwd_kernel4Args
    .private_segment_fixed_size: 0
    .sgpr_count:     108
    .sgpr_spill_count: 67
    .symbol:         _Z10fwd_kernel4Args.kd
    .uniform_work_group_size: 1
    .uses_dynamic_stack: false
    .vgpr_count:     256
    .vgpr_spill_count: 0
    .wavefront_size: 64
